# split the 32-long dependent softmax row-sum add chains in attention into two independent chains (on top of nt stores + static prio)
# baseline (speedup 1.0000x reference)
.LBB0_715:
	ds_read_b128 v[64:67], v166 offset:32768
	ds_read_b128 v[200:203], v166 offset:40960
	v_exp_f32_e32 v181, v48
	v_add_f32_e32 v48, 0, v183
	v_add_f32_e32 v216, 0, v185
	s_waitcnt lgkmcnt(1)
	v_mfma_f32_32x32x16_bf16 v[80:95], v[64:67], v[116:119], v[32:47]
	v_add_f32_e32 v48, v182, v48
	v_add_f32_e32 v216, v184, v216
	v_add_f32_e32 v48, v141, v48
	v_add_f32_e32 v216, v143, v216
	v_add_f32_e32 v48, v140, v48
	v_add_f32_e32 v216, v142, v216
	v_add_f32_e32 v48, v137, v48
	s_waitcnt lgkmcnt(0)
	v_mfma_f32_32x32x16_bf16 v[64:79], v[200:203], v[116:119], v[32:47]
	ds_read_b128 v[200:203], v167 offset:32768
	ds_read_b128 v[204:207], v167 offset:40960
	v_add_f32_e32 v216, v139, v216
	v_add_f32_e32 v48, v135, v48
	v_add_f32_e32 v216, v138, v216
	v_add_f32_e32 v48, v133, v48
	v_exp_f32_e32 v186, v49
	v_add_f32_e32 v216, v136, v216
	s_waitcnt lgkmcnt(1)
	v_mfma_f32_32x32x16_bf16 v[80:95], v[200:203], v[112:115], v[80:95]
	v_exp_f32_e32 v187, v50
	v_add_f32_e32 v48, v132, v48
	v_exp_f32_e32 v196, v51
	v_add_f32_e32 v216, v134, v216
	v_exp_f32_e32 v197, v52
	v_add_f32_e32 v48, v181, v48
	v_add_f32_e32 v216, v186, v216
	s_waitcnt lgkmcnt(0)
	v_mfma_f32_32x32x16_bf16 v[64:79], v[204:207], v[112:115], v[64:79]
	ds_read_b128 v[200:203], v169 offset:32768
	ds_read_b128 v[204:207], v169 offset:40960
	v_add_f32_e32 v48, v187, v48
	v_add_f32_e32 v216, v196, v216
	v_add_f32_e32 v48, v197, v48
	v_exp_f32_e32 v208, v61
	v_exp_f32_e32 v209, v62
	v_exp_f32_e32 v63, v63
	s_waitcnt lgkmcnt(1)
	v_mfma_f32_32x32x16_bf16 v[80:95], v[200:203], v[108:111], v[80:95]
	s_waitcnt lgkmcnt(0)
	v_mfma_f32_32x32x16_bf16 v[64:79], v[204:207], v[108:111], v[64:79]
	ds_read_b128 v[200:203], v170 offset:32768
	ds_read_b128 v[204:207], v170 offset:40960
	s_waitcnt lgkmcnt(1)
	v_mfma_f32_32x32x16_bf16 v[80:95], v[200:203], v[104:107], v[80:95]
	s_waitcnt lgkmcnt(0)
	v_mfma_f32_32x32x16_bf16 v[64:79], v[204:207], v[104:107], v[64:79]
	ds_read_b128 v[200:203], v168 offset:32768
	ds_read_b128 v[204:207], v168 offset:40960
	s_waitcnt lgkmcnt(1)
	v_mfma_f32_32x32x16_bf16 v[80:95], v[200:203], v[100:103], v[80:95]
	s_waitcnt lgkmcnt(0)
	v_mfma_f32_32x32x16_bf16 v[64:79], v[204:207], v[100:103], v[64:79]
	ds_read_b128 v[200:203], v171 offset:32768
	ds_read_b128 v[204:207], v171 offset:40960
	s_waitcnt lgkmcnt(1)
	v_mfma_f32_32x32x16_bf16 v[80:95], v[200:203], v[96:99], v[80:95]
	v_exp_f32_e32 v200, v53
	v_exp_f32_e32 v201, v54
	v_exp_f32_e32 v202, v55
	v_exp_f32_e32 v203, v56
	v_add_f32_e32 v216, v200, v216
	v_add_f32_e32 v48, v201, v48
	v_add_f32_e32 v216, v202, v216
	s_waitcnt lgkmcnt(0)
	v_mfma_f32_32x32x16_bf16 v[64:79], v[204:207], v[96:99], v[64:79]
	v_exp_f32_e32 v204, v57
	v_exp_f32_e32 v205, v58
	v_exp_f32_e32 v206, v59
	v_exp_f32_e32 v207, v60
	v_add_f32_e32 v48, v203, v48
	v_add_f32_e32 v216, v204, v216
	v_add_f32_e32 v48, v205, v48
	v_add_f32_e32 v216, v206, v216
	v_add_f32_e32 v48, v207, v48
	v_add_f32_e32 v216, v208, v216
	v_add_f32_e32 v48, v209, v48
	v_add_f32_e32 v48, v216, v48
	v_add_f32_e32 v179, v63, v48
	v_mov_b32_e32 v180, v179
	v_cvt_pk_bf16_f32 v48, v183, v185
	v_cvt_pk_bf16_f32 v49, v182, v184
	v_cvt_pk_bf16_f32 v50, v141, v143
	s_nop 1
	v_permlane32_swap_b32_e32 v179, v180
	v_cvt_pk_bf16_f32 v51, v140, v142
	v_permlane32_swap_b32_e32 v48, v50
	v_cvt_pk_bf16_f32 v52, v137, v139
	v_cvt_pk_bf16_f32 v53, v135, v138
	v_cvt_pk_bf16_f32 v54, v133, v136
	v_cvt_pk_bf16_f32 v55, v132, v134
	v_cvt_pk_bf16_f32 v56, v181, v186
	v_cvt_pk_bf16_f32 v57, v187, v196
	v_cvt_pk_bf16_f32 v58, v197, v200
	v_cvt_pk_bf16_f32 v59, v201, v202
	v_cvt_pk_bf16_f32 v60, v203, v204
	v_cvt_pk_bf16_f32 v61, v205, v206
	v_cvt_pk_bf16_f32 v62, v207, v208
	v_cvt_pk_bf16_f32 v63, v209, v63
	v_permlane32_swap_b32_e32 v49, v51
	v_permlane32_swap_b32_e32 v52, v54
	v_permlane32_swap_b32_e32 v53, v55
	v_permlane32_swap_b32_e32 v56, v58
	v_permlane32_swap_b32_e32 v57, v59
	v_permlane32_swap_b32_e32 v60, v62
	v_permlane32_swap_b32_e32 v61, v63
	s_movk_i32 s2, 0xffe0
	s_mov_b32 s3, -1
	v_lshl_add_u64 v[136:137], v[154:155], 0, s[2:3]
	v_lshlrev_b64 v[136:137], v172, v[136:137]
	v_lshlrev_b64 v[138:139], v172, v[154:155]
	v_lshl_add_u64 v[136:137], v[136:137], 1, v[144:145]
	v_lshl_add_u64 v[140:141], v[138:139], 1, v[144:145]
	global_load_dwordx4 v[132:135], v[158:159], off
	s_nop 0
	global_load_dwordx4 v[136:139], v[136:137], off
	s_nop 0
	global_load_dwordx4 v[140:143], v[140:141], off
	ds_read_b64_tr_b16 v[182:183], v175 offset:0
	ds_read_b64_tr_b16 v[184:185], v175 offset:0x400
	ds_read_b64_tr_b16 v[200:201], v175 offset:0x800
	ds_read_b64_tr_b16 v[202:203], v175 offset:0xc00
	ds_read_b64_tr_b16 v[204:205], v175 offset:0x1000
	ds_read_b64_tr_b16 v[206:207], v175 offset:0x1400
	ds_read_b64_tr_b16 v[208:209], v175 offset:0x1800
	ds_read_b64_tr_b16 v[210:211], v175 offset:0x1c00
	s_waitcnt lgkmcnt(0)
	s_nop 0
	v_mfma_f32_32x32x16_bf16 v[16:31], v[48:51], v[182:185], v[16:31]
	ds_read_b64_tr_b16 v[182:183], v175 offset:0x200
	ds_read_b64_tr_b16 v[184:185], v175 offset:0x600
	v_mfma_f32_32x32x16_bf16 v[16:31], v[52:55], v[200:203], v[16:31]
	ds_read_b64_tr_b16 v[200:201], v175 offset:0xa00
	ds_read_b64_tr_b16 v[202:203], v175 offset:0xe00
	v_mfma_f32_32x32x16_bf16 v[16:31], v[56:59], v[204:207], v[16:31]
	ds_read_b64_tr_b16 v[204:205], v175 offset:0x1200
	ds_read_b64_tr_b16 v[206:207], v175 offset:0x1600
	v_mfma_f32_32x32x16_bf16 v[16:31], v[60:63], v[208:211], v[16:31]
	ds_read_b64_tr_b16 v[208:209], v175 offset:0x1a00
	ds_read_b64_tr_b16 v[210:211], v175 offset:0x1e00
	s_waitcnt lgkmcnt(0)
	v_mfma_f32_32x32x16_bf16 v[0:15], v[48:51], v[182:185], v[0:15]
	v_max_f32_e32 v48, v81, v81
	v_max_f32_e32 v49, v80, v80
	v_max_f32_e32 v48, v49, v48
	v_max3_f32 v48, v48, v82, v83
	v_max3_f32 v48, v48, v84, v85
	v_max3_f32 v48, v48, v86, v87
	v_max3_f32 v48, v48, v88, v89
	v_mfma_f32_32x32x16_bf16 v[0:15], v[52:55], v[200:203], v[0:15]
	v_max3_f32 v48, v48, v90, v91
	v_max3_f32 v48, v48, v92, v93
	v_max3_f32 v48, v48, v94, v95
	v_max3_f32 v48, v48, v64, v65
	v_max3_f32 v48, v48, v66, v67
	v_max3_f32 v48, v48, v68, v69
	v_max3_f32 v48, v48, v70, v71
	v_mfma_f32_32x32x16_bf16 v[0:15], v[56:59], v[204:207], v[0:15]
	v_max3_f32 v48, v48, v72, v73
	v_max3_f32 v48, v48, v74, v75
	v_max3_f32 v48, v48, v76, v77
	v_max3_f32 v48, v48, v78, v79
	v_mov_b32_e32 v49, v48
	s_nop 1
	v_permlane32_swap_b32_e32 v48, v49
	v_mfma_f32_32x32x16_bf16 v[0:15], v[60:63], v[208:211], v[0:15]
	v_max_f32_e32 v49, v49, v49
	v_max_f32_e32 v48, v48, v48
	v_max_f32_e32 v48, v48, v49
	v_cmp_ge_f32_e32 vcc, s76, v48
	s_cmp_eq_u64 vcc, exec
	v_mov_b32_e32 v181, 1.0
	s_cbranch_scc0 .LBB0_727

.LBB0_720:
	v_exp_f32_e32 v131, v82
	v_exp_f32_e32 v129, v84
	v_exp_f32_e32 v128, v86
	v_exp_f32_e32 v130, v87
	v_exp_f32_e32 v125, v88
	v_exp_f32_e32 v127, v89
	v_exp_f32_e32 v123, v90
	v_exp_f32_e32 v126, v91
	v_exp_f32_e32 v121, v92
	v_exp_f32_e32 v124, v93
	v_exp_f32_e32 v120, v94
	v_exp_f32_e32 v122, v95
	v_exp_f32_e32 v183, v80
	v_exp_f32_e32 v185, v81
	v_exp_f32_e32 v184, v83
	v_exp_f32_e32 v182, v85
	s_waitcnt lgkmcnt(0)
	s_barrier
	ds_read_b128 v[48:51], v166 offset:16384
	ds_read_b128 v[200:203], v166 offset:24576
	v_exp_f32_e32 v186, v64
	v_add_f32_e32 v64, 0, v183
	v_add_f32_e32 v217, 0, v185
	s_waitcnt lgkmcnt(1)
	v_mfma_f32_32x32x16_bf16 v[80:95], v[48:51], v[116:119], v[32:47]
	v_add_f32_e32 v64, v131, v64
	v_add_f32_e32 v217, v184, v217
	v_add_f32_e32 v64, v129, v64
	v_add_f32_e32 v217, v182, v217
	v_add_f32_e32 v64, v128, v64
	v_add_f32_e32 v217, v130, v217
	v_add_f32_e32 v64, v125, v64
	s_waitcnt lgkmcnt(0)
	v_mfma_f32_32x32x16_bf16 v[48:63], v[200:203], v[116:119], v[32:47]
	ds_read_b128 v[200:203], v167 offset:16384
	ds_read_b128 v[204:207], v167 offset:24576
	v_add_f32_e32 v217, v127, v217
	v_add_f32_e32 v64, v123, v64
	v_add_f32_e32 v217, v126, v217
	v_add_f32_e32 v64, v121, v64
	v_exp_f32_e32 v187, v65
	v_add_f32_e32 v217, v124, v217
	s_waitcnt lgkmcnt(1)
	v_mfma_f32_32x32x16_bf16 v[80:95], v[200:203], v[112:115], v[80:95]
	v_exp_f32_e32 v196, v66
	v_add_f32_e32 v64, v120, v64
	v_exp_f32_e32 v197, v67
	v_add_f32_e32 v217, v122, v217
	v_add_f32_e32 v64, v186, v64
	v_add_f32_e32 v217, v187, v217
	v_add_f32_e32 v64, v196, v64
	s_waitcnt lgkmcnt(0)
	v_mfma_f32_32x32x16_bf16 v[48:63], v[204:207], v[112:115], v[48:63]
	ds_read_b128 v[200:203], v169 offset:16384
	ds_read_b128 v[204:207], v169 offset:24576
	v_add_f32_e32 v217, v197, v217
	v_exp_f32_e32 v208, v76
	v_exp_f32_e32 v209, v77
	v_exp_f32_e32 v78, v78
	v_exp_f32_e32 v79, v79
	s_waitcnt lgkmcnt(1)
	v_mfma_f32_32x32x16_bf16 v[80:95], v[200:203], v[108:111], v[80:95]
	s_waitcnt lgkmcnt(0)
	v_mfma_f32_32x32x16_bf16 v[48:63], v[204:207], v[108:111], v[48:63]
	ds_read_b128 v[200:203], v170 offset:16384
	ds_read_b128 v[204:207], v170 offset:24576
	s_waitcnt lgkmcnt(1)
	v_mfma_f32_32x32x16_bf16 v[80:95], v[200:203], v[104:107], v[80:95]
	s_waitcnt lgkmcnt(0)
	v_mfma_f32_32x32x16_bf16 v[48:63], v[204:207], v[104:107], v[48:63]
	ds_read_b128 v[200:203], v168 offset:16384
	ds_read_b128 v[204:207], v168 offset:24576
	s_waitcnt lgkmcnt(1)
	v_mfma_f32_32x32x16_bf16 v[80:95], v[200:203], v[100:103], v[80:95]
	s_waitcnt lgkmcnt(0)
	v_mfma_f32_32x32x16_bf16 v[48:63], v[204:207], v[100:103], v[48:63]
	ds_read_b128 v[200:203], v171 offset:16384
	ds_read_b128 v[204:207], v171 offset:24576
	v_cvt_pk_bf16_f32 v66, v183, v185
	v_cvt_pk_bf16_f32 v67, v131, v184
	s_waitcnt lgkmcnt(1)
	v_mfma_f32_32x32x16_bf16 v[80:95], v[200:203], v[96:99], v[80:95]
	v_exp_f32_e32 v200, v68
	v_exp_f32_e32 v201, v69
	v_exp_f32_e32 v202, v70
	v_exp_f32_e32 v203, v71
	v_add_f32_e32 v64, v200, v64
	v_add_f32_e32 v217, v201, v217
	v_add_f32_e32 v64, v202, v64
	s_waitcnt lgkmcnt(0)
	v_mfma_f32_32x32x16_bf16 v[48:63], v[204:207], v[96:99], v[48:63]
	v_exp_f32_e32 v204, v72
	v_exp_f32_e32 v205, v73
	v_exp_f32_e32 v206, v74
	v_exp_f32_e32 v207, v75
	v_add_f32_e32 v217, v203, v217
	v_add_f32_e32 v64, v204, v64
	v_add_f32_e32 v217, v205, v217
	v_add_f32_e32 v64, v206, v64
	v_add_f32_e32 v217, v207, v217
	v_add_f32_e32 v64, v208, v64
	v_add_f32_e32 v217, v209, v217
	v_add_f32_e32 v64, v78, v64
	v_add_f32_e32 v217, v79, v217
	v_add_f32_e32 v64, v217, v64
	v_mov_b32_e32 v65, v64
	v_cvt_pk_bf16_f32 v68, v129, v182
	v_cvt_pk_bf16_f32 v69, v128, v130
	s_nop 1
	v_permlane32_swap_b32_e32 v64, v65
	v_permlane32_swap_b32_e32 v66, v68
	v_permlane32_swap_b32_e32 v67, v69
	v_cvt_pk_bf16_f32 v70, v125, v127
	v_cvt_pk_bf16_f32 v71, v123, v126
	v_cvt_pk_bf16_f32 v72, v121, v124
	v_cvt_pk_bf16_f32 v73, v120, v122
	v_cvt_pk_bf16_f32 v74, v186, v187
	v_cvt_pk_bf16_f32 v75, v196, v197
	v_cvt_pk_bf16_f32 v76, v200, v201
	v_cvt_pk_bf16_f32 v77, v202, v203
	v_cvt_pk_bf16_f32 v182, v204, v205
	v_cvt_pk_bf16_f32 v183, v206, v207
	v_cvt_pk_bf16_f32 v184, v208, v209
	v_cvt_pk_bf16_f32 v185, v78, v79
	s_nop 0
	v_permlane32_swap_b32_e32 v70, v72
	v_permlane32_swap_b32_e32 v71, v73
	v_permlane32_swap_b32_e32 v74, v76
	v_permlane32_swap_b32_e32 v75, v77
	v_permlane32_swap_b32_e32 v182, v184
	v_permlane32_swap_b32_e32 v183, v185
	s_add_i32 s2, s59, -2
	s_min_u32 s2, s2, s58
	s_lshl_b32 s2, s2, 6
	v_add_u32_e32 v78, s2, v148
	v_ashrrev_i32_e32 v79, 31, v78
	v_lshlrev_b64 v[78:79], 7, v[78:79]
	v_lshl_add_u64 v[78:79], v[152:153], 0, v[78:79]
	global_load_dwordx4 v[120:123], v[78:79], off
	v_add_u32_e32 v78, s2, v146
	v_add_u32_e32 v124, s2, v150
	v_ashrrev_i32_e32 v79, 31, v78
	v_ashrrev_i32_e32 v125, 31, v124
	v_lshlrev_b64 v[78:79], v172, v[78:79]
	v_lshlrev_b64 v[124:125], v172, v[124:125]
	v_lshl_add_u64 v[78:79], v[78:79], 1, v[144:145]
	v_lshl_add_u64 v[128:129], v[124:125], 1, v[144:145]
	global_load_dwordx4 v[124:127], v[78:79], off
	s_nop 0
	global_load_dwordx4 v[128:131], v[128:129], off
	ds_read_b64_tr_b16 v[200:201], v157 offset:0
	ds_read_b64_tr_b16 v[202:203], v157 offset:0x400
	ds_read_b64_tr_b16 v[204:205], v157 offset:0x800
	ds_read_b64_tr_b16 v[206:207], v157 offset:0xc00
	ds_read_b64_tr_b16 v[208:209], v157 offset:0x1000
	ds_read_b64_tr_b16 v[210:211], v157 offset:0x1400
	ds_read_b64_tr_b16 v[212:213], v157 offset:0x1800
	ds_read_b64_tr_b16 v[214:215], v157 offset:0x1c00
	s_waitcnt lgkmcnt(0)
	s_nop 0
	v_mfma_f32_32x32x16_bf16 v[16:31], v[66:69], v[200:203], v[16:31]
	ds_read_b64_tr_b16 v[200:201], v157 offset:0x200
	ds_read_b64_tr_b16 v[202:203], v157 offset:0x600
	v_mfma_f32_32x32x16_bf16 v[16:31], v[70:73], v[204:207], v[16:31]
	ds_read_b64_tr_b16 v[204:205], v157 offset:0xa00
	ds_read_b64_tr_b16 v[206:207], v157 offset:0xe00
	v_mfma_f32_32x32x16_bf16 v[16:31], v[74:77], v[208:211], v[16:31]
	ds_read_b64_tr_b16 v[208:209], v157 offset:0x1200
	ds_read_b64_tr_b16 v[210:211], v157 offset:0x1600
	v_mfma_f32_32x32x16_bf16 v[16:31], v[182:185], v[212:215], v[16:31]
	ds_read_b64_tr_b16 v[212:213], v157 offset:0x1a00
	ds_read_b64_tr_b16 v[214:215], v157 offset:0x1e00
	s_waitcnt lgkmcnt(0)
	v_mfma_f32_32x32x16_bf16 v[0:15], v[66:69], v[200:203], v[0:15]
	v_max_f32_e32 v66, v81, v81
	v_max_f32_e32 v67, v80, v80
	v_max_f32_e32 v66, v67, v66
	v_max3_f32 v66, v66, v82, v83
	v_max3_f32 v66, v66, v84, v85
	v_max3_f32 v66, v66, v86, v87
	v_max3_f32 v66, v66, v88, v89
	v_mfma_f32_32x32x16_bf16 v[0:15], v[70:73], v[204:207], v[0:15]
	v_max3_f32 v66, v66, v90, v91
	v_max3_f32 v66, v66, v92, v93
	v_max3_f32 v66, v66, v94, v95
	v_max3_f32 v66, v66, v48, v49
	v_max3_f32 v66, v66, v50, v51
	v_max3_f32 v66, v66, v52, v53
	v_max3_f32 v66, v66, v54, v55
	v_mfma_f32_32x32x16_bf16 v[0:15], v[74:77], v[208:211], v[0:15]
	v_max3_f32 v66, v66, v56, v57
	v_max3_f32 v66, v66, v58, v59
	v_max3_f32 v66, v66, v60, v61
	v_max3_f32 v66, v66, v62, v63
	v_mov_b32_e32 v67, v66
	s_nop 1
	v_permlane32_swap_b32_e32 v66, v67
	v_mfma_f32_32x32x16_bf16 v[0:15], v[182:185], v[212:215], v[0:15]
	v_max_f32_e32 v67, v67, v67
	v_max_f32_e32 v66, v66, v66
	v_max_f32_e32 v67, v66, v67
	v_cmp_ge_f32_e32 vcc, s76, v67
	s_cmp_eq_u64 vcc, exec
	v_mov_b32_e32 v66, 1.0
	s_cbranch_scc0 .LBB0_728

.LBB0_733:
	ds_read_b128 v[200:203], v166 offset:32768
	ds_read_b128 v[204:207], v166 offset:40960
	s_cmp_le_i32 s2, s21
	s_cselect_b64 vcc, -1, 0
	v_cndmask_b32_e32 v79, v229, v47, vcc
	v_cndmask_b32_e32 v78, v229, v46, vcc
	v_cndmask_b32_e32 v77, v229, v45, vcc
	v_cndmask_b32_e32 v76, v229, v44, vcc
	v_cndmask_b32_e32 v75, v229, v43, vcc
	v_cndmask_b32_e32 v74, v229, v42, vcc
	v_cndmask_b32_e32 v73, v229, v41, vcc
	v_cndmask_b32_e32 v72, v229, v40, vcc
	v_cndmask_b32_e32 v71, v229, v39, vcc
	v_cndmask_b32_e32 v70, v229, v38, vcc
	v_cndmask_b32_e32 v69, v229, v37, vcc
	v_cndmask_b32_e32 v68, v229, v36, vcc
	v_cndmask_b32_e32 v67, v229, v35, vcc
	v_cndmask_b32_e32 v66, v229, v34, vcc
	v_cndmask_b32_e32 v65, v229, v33, vcc
	v_cndmask_b32_e32 v64, v229, v32, vcc
	v_exp_f32_e32 v181, v48
	v_add_f32_e32 v48, 0, v183
	s_waitcnt lgkmcnt(1)
	v_mfma_f32_32x32x16_bf16 v[80:95], v[200:203], v[116:119], v[64:79]
	v_add_f32_e32 v216, 0, v185
	v_add_f32_e32 v48, v182, v48
	v_add_f32_e32 v216, v184, v216
	v_add_f32_e32 v48, v141, v48
	v_add_f32_e32 v216, v143, v216
	v_add_f32_e32 v48, v140, v48
	v_add_f32_e32 v216, v142, v216
	s_waitcnt lgkmcnt(0)
	v_mfma_f32_32x32x16_bf16 v[64:79], v[204:207], v[116:119], v[64:79]
	ds_read_b128 v[200:203], v167 offset:32768
	ds_read_b128 v[204:207], v167 offset:40960
	v_add_f32_e32 v48, v137, v48
	v_add_f32_e32 v216, v139, v216
	v_add_f32_e32 v48, v135, v48
	v_add_f32_e32 v216, v138, v216
	v_add_f32_e32 v48, v133, v48
	v_exp_f32_e32 v186, v49
	s_waitcnt lgkmcnt(1)
	v_mfma_f32_32x32x16_bf16 v[80:95], v[200:203], v[112:115], v[80:95]
	v_add_f32_e32 v216, v136, v216
	v_exp_f32_e32 v187, v50
	v_add_f32_e32 v48, v132, v48
	v_exp_f32_e32 v196, v51
	v_add_f32_e32 v216, v134, v216
	v_exp_f32_e32 v197, v52
	v_add_f32_e32 v48, v181, v48
	s_waitcnt lgkmcnt(0)
	v_mfma_f32_32x32x16_bf16 v[64:79], v[204:207], v[112:115], v[64:79]
	ds_read_b128 v[200:203], v169 offset:32768
	ds_read_b128 v[204:207], v169 offset:40960
	v_add_f32_e32 v216, v186, v216
	v_add_f32_e32 v48, v187, v48
	v_add_f32_e32 v216, v196, v216
	v_add_f32_e32 v48, v197, v48
	v_exp_f32_e32 v208, v61
	v_exp_f32_e32 v209, v62
	s_waitcnt lgkmcnt(1)
	v_mfma_f32_32x32x16_bf16 v[80:95], v[200:203], v[108:111], v[80:95]
	v_exp_f32_e32 v63, v63
	s_waitcnt lgkmcnt(0)
	v_mfma_f32_32x32x16_bf16 v[64:79], v[204:207], v[108:111], v[64:79]
	ds_read_b128 v[200:203], v170 offset:32768
	ds_read_b128 v[204:207], v170 offset:40960
	s_waitcnt lgkmcnt(1)
	v_mfma_f32_32x32x16_bf16 v[80:95], v[200:203], v[104:107], v[80:95]
	s_waitcnt lgkmcnt(0)
	v_mfma_f32_32x32x16_bf16 v[64:79], v[204:207], v[104:107], v[64:79]
	ds_read_b128 v[200:203], v168 offset:32768
	ds_read_b128 v[204:207], v168 offset:40960
	s_waitcnt lgkmcnt(1)
	v_mfma_f32_32x32x16_bf16 v[80:95], v[200:203], v[100:103], v[80:95]
	s_waitcnt lgkmcnt(0)
	v_mfma_f32_32x32x16_bf16 v[64:79], v[204:207], v[100:103], v[64:79]
	ds_read_b128 v[200:203], v171 offset:32768
	ds_read_b128 v[204:207], v171 offset:40960
	s_waitcnt lgkmcnt(1)
	v_mfma_f32_32x32x16_bf16 v[80:95], v[200:203], v[96:99], v[80:95]
	v_exp_f32_e32 v200, v53
	v_exp_f32_e32 v201, v54
	v_exp_f32_e32 v202, v55
	v_exp_f32_e32 v203, v56
	v_add_f32_e32 v216, v200, v216
	v_add_f32_e32 v48, v201, v48
	v_add_f32_e32 v216, v202, v216
	s_waitcnt lgkmcnt(0)
	v_mfma_f32_32x32x16_bf16 v[64:79], v[204:207], v[96:99], v[64:79]
	v_exp_f32_e32 v204, v57
	v_exp_f32_e32 v205, v58
	v_exp_f32_e32 v206, v59
	v_exp_f32_e32 v207, v60
	v_add_f32_e32 v48, v203, v48
	v_add_f32_e32 v216, v204, v216
	v_add_f32_e32 v48, v205, v48
	v_add_f32_e32 v216, v206, v216
	v_add_f32_e32 v48, v207, v48
	v_add_f32_e32 v216, v208, v216
	v_add_f32_e32 v48, v209, v48
	v_add_f32_e32 v48, v216, v48
	v_add_f32_e32 v179, v63, v48
	v_mov_b32_e32 v180, v179
	v_cvt_pk_bf16_f32 v48, v183, v185
	v_cvt_pk_bf16_f32 v49, v182, v184
	v_cvt_pk_bf16_f32 v50, v141, v143
	s_nop 1
	v_permlane32_swap_b32_e32 v179, v180
	v_cvt_pk_bf16_f32 v51, v140, v142
	v_permlane32_swap_b32_e32 v48, v50
	v_cvt_pk_bf16_f32 v52, v137, v139
	v_cvt_pk_bf16_f32 v53, v135, v138
	v_cvt_pk_bf16_f32 v54, v133, v136
	v_cvt_pk_bf16_f32 v55, v132, v134
	v_cvt_pk_bf16_f32 v56, v181, v186
	v_cvt_pk_bf16_f32 v57, v187, v196
	v_cvt_pk_bf16_f32 v58, v197, v200
	v_cvt_pk_bf16_f32 v59, v201, v202
	v_cvt_pk_bf16_f32 v60, v203, v204
	v_cvt_pk_bf16_f32 v61, v205, v206
	v_cvt_pk_bf16_f32 v62, v207, v208
	v_cvt_pk_bf16_f32 v63, v209, v63
	v_permlane32_swap_b32_e32 v49, v51
	v_permlane32_swap_b32_e32 v52, v54
	v_permlane32_swap_b32_e32 v53, v55
	v_permlane32_swap_b32_e32 v56, v58
	v_permlane32_swap_b32_e32 v57, v59
	v_permlane32_swap_b32_e32 v60, v62
	v_permlane32_swap_b32_e32 v61, v63
	v_lshlrev_b64 v[136:137], v172, v[158:159]
	v_lshlrev_b64 v[138:139], v172, v[156:157]
	v_lshl_add_u64 v[136:137], v[136:137], 1, v[144:145]
	v_lshl_add_u64 v[140:141], v[138:139], 1, v[144:145]
	global_load_dwordx4 v[132:135], v[160:161], off
	s_nop 0
	global_load_dwordx4 v[136:139], v[136:137], off
	s_nop 0
	global_load_dwordx4 v[140:143], v[140:141], off
	ds_read_b64_tr_b16 v[182:183], v175 offset:0
	ds_read_b64_tr_b16 v[184:185], v175 offset:0x400
	ds_read_b64_tr_b16 v[200:201], v175 offset:0x800
	ds_read_b64_tr_b16 v[202:203], v175 offset:0xc00
	ds_read_b64_tr_b16 v[204:205], v175 offset:0x1000
	ds_read_b64_tr_b16 v[206:207], v175 offset:0x1400
	ds_read_b64_tr_b16 v[208:209], v175 offset:0x1800
	ds_read_b64_tr_b16 v[210:211], v175 offset:0x1c00
	s_waitcnt lgkmcnt(0)
	s_nop 0
	v_mfma_f32_32x32x16_bf16 v[16:31], v[48:51], v[182:185], v[16:31]
	ds_read_b64_tr_b16 v[182:183], v175 offset:0x200
	ds_read_b64_tr_b16 v[184:185], v175 offset:0x600
	v_mfma_f32_32x32x16_bf16 v[16:31], v[52:55], v[200:203], v[16:31]
	ds_read_b64_tr_b16 v[200:201], v175 offset:0xa00
	ds_read_b64_tr_b16 v[202:203], v175 offset:0xe00
	v_mfma_f32_32x32x16_bf16 v[16:31], v[56:59], v[204:207], v[16:31]
	ds_read_b64_tr_b16 v[204:205], v175 offset:0x1200
	ds_read_b64_tr_b16 v[206:207], v175 offset:0x1600
	v_mfma_f32_32x32x16_bf16 v[16:31], v[60:63], v[208:211], v[16:31]
	ds_read_b64_tr_b16 v[208:209], v175 offset:0x1a00
	ds_read_b64_tr_b16 v[210:211], v175 offset:0x1e00
	s_waitcnt lgkmcnt(0)
	v_mfma_f32_32x32x16_bf16 v[0:15], v[48:51], v[182:185], v[0:15]
	v_max_f32_e32 v48, v81, v81
	v_max_f32_e32 v49, v80, v80
	v_max_f32_e32 v48, v49, v48
	v_max3_f32 v48, v48, v82, v83
	v_max3_f32 v48, v48, v84, v85
	v_max3_f32 v48, v48, v86, v87
	v_max3_f32 v48, v48, v88, v89
	v_mfma_f32_32x32x16_bf16 v[0:15], v[52:55], v[200:203], v[0:15]
	v_max3_f32 v48, v48, v90, v91
	v_max3_f32 v48, v48, v92, v93
	v_max3_f32 v48, v48, v94, v95
	v_max3_f32 v48, v48, v64, v65
	v_max3_f32 v48, v48, v66, v67
	v_max3_f32 v48, v48, v68, v69
	v_max3_f32 v48, v48, v70, v71
	v_mfma_f32_32x32x16_bf16 v[0:15], v[56:59], v[204:207], v[0:15]
	v_max3_f32 v48, v48, v72, v73
	v_max3_f32 v48, v48, v74, v75
	v_max3_f32 v48, v48, v76, v77
	v_max3_f32 v48, v48, v78, v79
	v_mov_b32_e32 v49, v48
	s_nop 1
	v_permlane32_swap_b32_e32 v48, v49
	v_mfma_f32_32x32x16_bf16 v[0:15], v[60:63], v[208:211], v[0:15]
	v_max_f32_e32 v49, v49, v49
	v_max_f32_e32 v48, v48, v48
	v_max_f32_e32 v48, v48, v49
	v_cmp_ge_f32_e32 vcc, s76, v48
	s_cmp_eq_u64 vcc, exec
	v_mov_b32_e32 v186, 1.0
	s_cbranch_scc0 .LBB0_745

.LBB0_738:
	v_exp_f32_e32 v181, v82
	v_exp_f32_e32 v129, v84
	v_exp_f32_e32 v131, v85
	v_exp_f32_e32 v128, v86
	v_exp_f32_e32 v130, v87
	v_exp_f32_e32 v125, v88
	v_exp_f32_e32 v127, v89
	v_exp_f32_e32 v123, v90
	v_exp_f32_e32 v126, v91
	v_exp_f32_e32 v121, v92
	v_exp_f32_e32 v124, v93
	v_exp_f32_e32 v120, v94
	v_exp_f32_e32 v122, v95
	v_exp_f32_e32 v182, v80
	v_exp_f32_e32 v184, v81
	v_exp_f32_e32 v183, v83
	s_add_i32 s0, s2, 1
	s_waitcnt lgkmcnt(0)
	s_barrier
	ds_read_b128 v[200:203], v166 offset:16384
	ds_read_b128 v[204:207], v166 offset:24576
	s_cmp_le_i32 s0, s21
	s_cselect_b64 vcc, -1, 0
	v_cndmask_b32_e32 v63, v229, v47, vcc
	v_cndmask_b32_e32 v62, v229, v46, vcc
	v_cndmask_b32_e32 v61, v229, v45, vcc
	v_cndmask_b32_e32 v60, v229, v44, vcc
	v_cndmask_b32_e32 v59, v229, v43, vcc
	v_cndmask_b32_e32 v58, v229, v42, vcc
	v_cndmask_b32_e32 v57, v229, v41, vcc
	v_cndmask_b32_e32 v56, v229, v40, vcc
	v_cndmask_b32_e32 v55, v229, v39, vcc
	v_cndmask_b32_e32 v54, v229, v38, vcc
	v_cndmask_b32_e32 v53, v229, v37, vcc
	v_cndmask_b32_e32 v52, v229, v36, vcc
	v_cndmask_b32_e32 v51, v229, v35, vcc
	v_cndmask_b32_e32 v50, v229, v34, vcc
	v_cndmask_b32_e32 v49, v229, v33, vcc
	v_cndmask_b32_e32 v48, v229, v32, vcc
	v_exp_f32_e32 v185, v64
	v_add_f32_e32 v64, 0, v182
	s_waitcnt lgkmcnt(1)
	v_mfma_f32_32x32x16_bf16 v[80:95], v[200:203], v[116:119], v[48:63]
	v_add_f32_e32 v217, 0, v184
	v_add_f32_e32 v64, v181, v64
	v_add_f32_e32 v217, v183, v217
	v_add_f32_e32 v64, v129, v64
	v_add_f32_e32 v217, v131, v217
	v_add_f32_e32 v64, v128, v64
	v_add_f32_e32 v217, v130, v217
	s_waitcnt lgkmcnt(0)
	v_mfma_f32_32x32x16_bf16 v[48:63], v[204:207], v[116:119], v[48:63]
	ds_read_b128 v[200:203], v167 offset:16384
	ds_read_b128 v[204:207], v167 offset:24576
	v_add_f32_e32 v64, v125, v64
	v_add_f32_e32 v217, v127, v217
	v_add_f32_e32 v64, v123, v64
	v_add_f32_e32 v217, v126, v217
	v_add_f32_e32 v64, v121, v64
	v_exp_f32_e32 v187, v65
	s_waitcnt lgkmcnt(1)
	v_mfma_f32_32x32x16_bf16 v[80:95], v[200:203], v[112:115], v[80:95]
	v_add_f32_e32 v217, v124, v217
	v_exp_f32_e32 v196, v66
	v_add_f32_e32 v64, v120, v64
	v_exp_f32_e32 v197, v67
	v_add_f32_e32 v217, v122, v217
	v_add_f32_e32 v64, v185, v64
	v_add_f32_e32 v217, v187, v217
	s_waitcnt lgkmcnt(0)
	v_mfma_f32_32x32x16_bf16 v[48:63], v[204:207], v[112:115], v[48:63]
	ds_read_b128 v[200:203], v169 offset:16384
	ds_read_b128 v[204:207], v169 offset:24576
	v_add_f32_e32 v64, v196, v64
	v_add_f32_e32 v217, v197, v217
	v_exp_f32_e32 v208, v76
	v_exp_f32_e32 v209, v77
	v_exp_f32_e32 v78, v78
	v_exp_f32_e32 v79, v79
	s_waitcnt lgkmcnt(1)
	v_mfma_f32_32x32x16_bf16 v[80:95], v[200:203], v[108:111], v[80:95]
	s_waitcnt lgkmcnt(0)
	v_mfma_f32_32x32x16_bf16 v[48:63], v[204:207], v[108:111], v[48:63]
	ds_read_b128 v[200:203], v170 offset:16384
	ds_read_b128 v[204:207], v170 offset:24576
	s_waitcnt lgkmcnt(1)
	v_mfma_f32_32x32x16_bf16 v[80:95], v[200:203], v[104:107], v[80:95]
	s_waitcnt lgkmcnt(0)
	v_mfma_f32_32x32x16_bf16 v[48:63], v[204:207], v[104:107], v[48:63]
	ds_read_b128 v[200:203], v168 offset:16384
	ds_read_b128 v[204:207], v168 offset:24576
	s_waitcnt lgkmcnt(1)
	v_mfma_f32_32x32x16_bf16 v[80:95], v[200:203], v[100:103], v[80:95]
	s_waitcnt lgkmcnt(0)
	v_mfma_f32_32x32x16_bf16 v[48:63], v[204:207], v[100:103], v[48:63]
	ds_read_b128 v[200:203], v171 offset:16384
	ds_read_b128 v[204:207], v171 offset:24576
	v_cvt_pk_bf16_f32 v66, v182, v184
	v_cvt_pk_bf16_f32 v67, v181, v183
	s_waitcnt lgkmcnt(1)
	v_mfma_f32_32x32x16_bf16 v[80:95], v[200:203], v[96:99], v[80:95]
	v_exp_f32_e32 v200, v68
	v_exp_f32_e32 v201, v69
	v_exp_f32_e32 v202, v70
	v_exp_f32_e32 v203, v71
	v_add_f32_e32 v64, v200, v64
	v_add_f32_e32 v217, v201, v217
	v_add_f32_e32 v64, v202, v64
	s_waitcnt lgkmcnt(0)
	v_mfma_f32_32x32x16_bf16 v[48:63], v[204:207], v[96:99], v[48:63]
	v_exp_f32_e32 v204, v72
	v_exp_f32_e32 v205, v73
	v_exp_f32_e32 v206, v74
	v_exp_f32_e32 v207, v75
	v_add_f32_e32 v217, v203, v217
	v_add_f32_e32 v64, v204, v64
	v_add_f32_e32 v217, v205, v217
	v_add_f32_e32 v64, v206, v64
	v_add_f32_e32 v217, v207, v217
	v_add_f32_e32 v64, v208, v64
	v_add_f32_e32 v217, v209, v217
	v_add_f32_e32 v64, v78, v64
	v_add_f32_e32 v217, v79, v217
	v_add_f32_e32 v64, v217, v64
	v_mov_b32_e32 v65, v64
	v_cvt_pk_bf16_f32 v68, v129, v131
	s_nop 1
	v_permlane32_swap_b32_e32 v64, v65
	v_cvt_pk_bf16_f32 v69, v128, v130
	v_permlane32_swap_b32_e32 v66, v68
	v_cvt_pk_bf16_f32 v70, v125, v127
	v_cvt_pk_bf16_f32 v71, v123, v126
	v_cvt_pk_bf16_f32 v72, v121, v124
	v_cvt_pk_bf16_f32 v73, v120, v122
	v_cvt_pk_bf16_f32 v74, v185, v187
	v_cvt_pk_bf16_f32 v75, v196, v197
	v_cvt_pk_bf16_f32 v76, v200, v201
	v_cvt_pk_bf16_f32 v77, v202, v203
	v_cvt_pk_bf16_f32 v182, v204, v205
	v_cvt_pk_bf16_f32 v183, v206, v207
	v_cvt_pk_bf16_f32 v184, v208, v209
	v_cvt_pk_bf16_f32 v185, v78, v79
	v_permlane32_swap_b32_e32 v67, v69
	v_permlane32_swap_b32_e32 v70, v72
	v_permlane32_swap_b32_e32 v71, v73
	v_permlane32_swap_b32_e32 v74, v76
	v_permlane32_swap_b32_e32 v75, v77
	v_permlane32_swap_b32_e32 v182, v184
	v_permlane32_swap_b32_e32 v183, v185
	s_add_i32 s60, s2, 3
	s_min_u32 s0, s60, s57
	s_lshl_b32 s0, s0, 6
	v_add_u32_e32 v78, s0, v148
	v_ashrrev_i32_e32 v79, 31, v78
	v_lshlrev_b64 v[78:79], 7, v[78:79]
	v_lshl_add_u64 v[78:79], v[152:153], 0, v[78:79]
	global_load_dwordx4 v[120:123], v[78:79], off
	v_add_u32_e32 v78, s0, v146
	v_add_u32_e32 v124, s0, v150
	v_ashrrev_i32_e32 v79, 31, v78
	v_ashrrev_i32_e32 v125, 31, v124
	v_lshlrev_b64 v[78:79], v172, v[78:79]
	v_lshlrev_b64 v[124:125], v172, v[124:125]
	v_lshl_add_u64 v[78:79], v[78:79], 1, v[144:145]
	v_lshl_add_u64 v[128:129], v[124:125], 1, v[144:145]
	global_load_dwordx4 v[124:127], v[78:79], off
	s_nop 0
	global_load_dwordx4 v[128:131], v[128:129], off
	ds_read_b64_tr_b16 v[200:201], v155 offset:0
	ds_read_b64_tr_b16 v[202:203], v155 offset:0x400
	ds_read_b64_tr_b16 v[204:205], v155 offset:0x800
	ds_read_b64_tr_b16 v[206:207], v155 offset:0xc00
	ds_read_b64_tr_b16 v[208:209], v155 offset:0x1000
	ds_read_b64_tr_b16 v[210:211], v155 offset:0x1400
	ds_read_b64_tr_b16 v[212:213], v155 offset:0x1800
	ds_read_b64_tr_b16 v[214:215], v155 offset:0x1c00
	s_waitcnt lgkmcnt(0)
	s_nop 0
	v_mfma_f32_32x32x16_bf16 v[16:31], v[66:69], v[200:203], v[16:31]
	ds_read_b64_tr_b16 v[200:201], v155 offset:0x200
	ds_read_b64_tr_b16 v[202:203], v155 offset:0x600
	v_mfma_f32_32x32x16_bf16 v[16:31], v[70:73], v[204:207], v[16:31]
	ds_read_b64_tr_b16 v[204:205], v155 offset:0xa00
	ds_read_b64_tr_b16 v[206:207], v155 offset:0xe00
	v_mfma_f32_32x32x16_bf16 v[16:31], v[74:77], v[208:211], v[16:31]
	ds_read_b64_tr_b16 v[208:209], v155 offset:0x1200
	ds_read_b64_tr_b16 v[210:211], v155 offset:0x1600
	v_mfma_f32_32x32x16_bf16 v[16:31], v[182:185], v[212:215], v[16:31]
	ds_read_b64_tr_b16 v[212:213], v155 offset:0x1a00
	ds_read_b64_tr_b16 v[214:215], v155 offset:0x1e00
	s_waitcnt lgkmcnt(0)
	v_mfma_f32_32x32x16_bf16 v[0:15], v[66:69], v[200:203], v[0:15]
	v_max_f32_e32 v66, v81, v81
	v_max_f32_e32 v67, v80, v80
	v_max_f32_e32 v66, v67, v66
	v_max3_f32 v66, v66, v82, v83
	v_max3_f32 v66, v66, v84, v85
	v_max3_f32 v66, v66, v86, v87
	v_max3_f32 v66, v66, v88, v89
	v_mfma_f32_32x32x16_bf16 v[0:15], v[70:73], v[204:207], v[0:15]
	v_max3_f32 v66, v66, v90, v91
	v_max3_f32 v66, v66, v92, v93
	v_max3_f32 v66, v66, v94, v95
	v_max3_f32 v66, v66, v48, v49
	v_max3_f32 v66, v66, v50, v51
	v_max3_f32 v66, v66, v52, v53
	v_max3_f32 v66, v66, v54, v55
	v_mfma_f32_32x32x16_bf16 v[0:15], v[74:77], v[208:211], v[0:15]
	v_max3_f32 v66, v66, v56, v57
	v_max3_f32 v66, v66, v58, v59
	v_max3_f32 v66, v66, v60, v61
	v_max3_f32 v66, v66, v62, v63
	v_mov_b32_e32 v67, v66
	s_nop 1
	v_permlane32_swap_b32_e32 v66, v67
	v_mfma_f32_32x32x16_bf16 v[0:15], v[182:185], v[212:215], v[0:15]
	v_max_f32_e32 v67, v67, v67
	v_max_f32_e32 v66, v66, v66
	v_max_f32_e32 v66, v66, v67
	v_cmp_ge_f32_e32 vcc, s76, v66
	s_cmp_eq_u64 vcc, exec
	v_mov_b32_e32 v181, 1.0
	s_cbranch_scc0 .LBB0_746

.LBB0_748:
	ds_read_b128 v[80:83], v166 offset:32768
	ds_read_b128 v[84:87], v166 offset:40960
	s_cmp_gt_i32 s3, 2
	s_cselect_b64 vcc, -1, 0
	v_cndmask_b32_e32 v47, v229, v47, vcc
	v_cndmask_b32_e32 v46, v229, v46, vcc
	v_cndmask_b32_e32 v45, v229, v45, vcc
	v_cndmask_b32_e32 v44, v229, v44, vcc
	v_cndmask_b32_e32 v43, v229, v43, vcc
	v_cndmask_b32_e32 v42, v229, v42, vcc
	v_cndmask_b32_e32 v41, v229, v41, vcc
	v_cndmask_b32_e32 v40, v229, v40, vcc
	v_cndmask_b32_e32 v39, v229, v39, vcc
	v_cndmask_b32_e32 v38, v229, v38, vcc
	v_cndmask_b32_e32 v37, v229, v37, vcc
	v_cndmask_b32_e32 v36, v229, v36, vcc
	v_cndmask_b32_e32 v35, v229, v35, vcc
	v_cndmask_b32_e32 v34, v229, v34, vcc
	v_cndmask_b32_e32 v33, v229, v33, vcc
	v_cndmask_b32_e32 v32, v229, v32, vcc
	v_exp_f32_e32 v88, v56
	v_exp_f32_e32 v89, v57
	s_waitcnt lgkmcnt(1)
	v_mfma_f32_32x32x16_bf16 v[64:79], v[80:83], v[116:119], v[32:47]
	v_exp_f32_e32 v90, v58
	v_exp_f32_e32 v91, v59
	v_exp_f32_e32 v92, v60
	v_exp_f32_e32 v93, v61
	v_exp_f32_e32 v62, v62
	v_exp_f32_e32 v63, v63
	s_waitcnt lgkmcnt(0)
	v_mfma_f32_32x32x16_bf16 v[32:47], v[84:87], v[116:119], v[32:47]
	ds_read_b128 v[80:83], v167 offset:32768
	ds_read_b128 v[84:87], v167 offset:40960
	s_waitcnt lgkmcnt(1)
	v_mfma_f32_32x32x16_bf16 v[64:79], v[80:83], v[112:115], v[64:79]
	s_waitcnt lgkmcnt(0)
	v_mfma_f32_32x32x16_bf16 v[32:47], v[84:87], v[112:115], v[32:47]
	ds_read_b128 v[80:83], v169 offset:32768
	ds_read_b128 v[84:87], v169 offset:40960
	s_waitcnt lgkmcnt(1)
	v_mfma_f32_32x32x16_bf16 v[64:79], v[80:83], v[108:111], v[64:79]
	s_waitcnt lgkmcnt(0)
	v_mfma_f32_32x32x16_bf16 v[32:47], v[84:87], v[108:111], v[32:47]
	ds_read_b128 v[80:83], v170 offset:32768
	ds_read_b128 v[84:87], v170 offset:40960
	s_waitcnt lgkmcnt(1)
	v_mfma_f32_32x32x16_bf16 v[64:79], v[80:83], v[104:107], v[64:79]
	s_waitcnt lgkmcnt(0)
	v_mfma_f32_32x32x16_bf16 v[32:47], v[84:87], v[104:107], v[32:47]
	ds_read_b128 v[80:83], v168 offset:32768
	ds_read_b128 v[84:87], v168 offset:40960
	s_waitcnt lgkmcnt(1)
	v_mfma_f32_32x32x16_bf16 v[64:79], v[80:83], v[100:103], v[64:79]
	s_waitcnt lgkmcnt(0)
	v_mfma_f32_32x32x16_bf16 v[32:47], v[84:87], v[100:103], v[32:47]
	ds_read_b128 v[80:83], v171 offset:32768
	ds_read_b128 v[84:87], v171 offset:40960
	s_waitcnt lgkmcnt(1)
	v_mfma_f32_32x32x16_bf16 v[64:79], v[80:83], v[96:99], v[64:79]
	v_exp_f32_e32 v80, v48
	v_add_f32_e32 v48, 0, v183
	v_add_f32_e32 v216, 0, v185
	v_add_f32_e32 v48, v182, v48
	v_add_f32_e32 v216, v184, v216
	v_add_f32_e32 v48, v141, v48
	v_add_f32_e32 v216, v143, v216
	v_add_f32_e32 v48, v140, v48
	v_add_f32_e32 v216, v142, v216
	v_add_f32_e32 v48, v137, v48
	v_add_f32_e32 v216, v139, v216
	v_add_f32_e32 v48, v135, v48
	v_add_f32_e32 v216, v138, v216
	v_add_f32_e32 v48, v133, v48
	v_exp_f32_e32 v81, v49
	v_add_f32_e32 v216, v136, v216
	v_exp_f32_e32 v82, v50
	v_add_f32_e32 v48, v132, v48
	v_exp_f32_e32 v83, v51
	v_add_f32_e32 v216, v134, v216
	s_waitcnt lgkmcnt(0)
	v_mfma_f32_32x32x16_bf16 v[32:47], v[84:87], v[96:99], v[32:47]
	v_exp_f32_e32 v84, v52
	v_add_f32_e32 v48, v80, v48
	v_exp_f32_e32 v85, v53
	v_add_f32_e32 v216, v81, v216
	v_exp_f32_e32 v86, v54
	v_add_f32_e32 v48, v82, v48
	v_exp_f32_e32 v87, v55
	v_add_f32_e32 v216, v83, v216
	v_add_f32_e32 v48, v84, v48
	v_add_f32_e32 v216, v85, v216
	v_add_f32_e32 v48, v86, v48
	v_add_f32_e32 v216, v87, v216
	v_add_f32_e32 v48, v88, v48
	v_add_f32_e32 v216, v89, v216
	v_add_f32_e32 v48, v90, v48
	v_add_f32_e32 v216, v91, v216
	v_add_f32_e32 v48, v92, v48
	v_add_f32_e32 v216, v93, v216
	v_add_f32_e32 v48, v62, v48
	v_add_f32_e32 v216, v63, v216
	v_add_f32_e32 v48, v216, v48
	v_mov_b32_e32 v49, v48
	v_cvt_pk_bf16_f32 v50, v183, v185
	v_cvt_pk_bf16_f32 v51, v182, v184
	v_cvt_pk_bf16_f32 v52, v141, v143
	v_cvt_pk_bf16_f32 v53, v140, v142
	s_nop 1
	v_permlane32_swap_b32_e32 v48, v49
	v_permlane32_swap_b32_e32 v50, v52
	v_permlane32_swap_b32_e32 v51, v53
	v_cvt_pk_bf16_f32 v54, v137, v139
	v_cvt_pk_bf16_f32 v55, v135, v138
	v_cvt_pk_bf16_f32 v56, v133, v136
	v_cvt_pk_bf16_f32 v57, v132, v134
	v_cvt_pk_bf16_f32 v58, v80, v81
	v_cvt_pk_bf16_f32 v59, v82, v83
	v_cvt_pk_bf16_f32 v60, v84, v85
	v_cvt_pk_bf16_f32 v61, v86, v87
	v_cvt_pk_bf16_f32 v80, v88, v89
	v_cvt_pk_bf16_f32 v81, v90, v91
	v_cvt_pk_bf16_f32 v82, v92, v93
	v_cvt_pk_bf16_f32 v83, v62, v63
	s_nop 0
	v_permlane32_swap_b32_e32 v54, v56
	v_permlane32_swap_b32_e32 v55, v57
	v_permlane32_swap_b32_e32 v58, v60
	v_permlane32_swap_b32_e32 v59, v61
	v_permlane32_swap_b32_e32 v80, v82
	v_permlane32_swap_b32_e32 v81, v83
	ds_read_b64_tr_b16 v[84:85], v175 offset:0
	ds_read_b64_tr_b16 v[86:87], v175 offset:0x400
	ds_read_b64_tr_b16 v[88:89], v175 offset:0x800
	ds_read_b64_tr_b16 v[90:91], v175 offset:0xc00
	ds_read_b64_tr_b16 v[92:93], v175 offset:0x1000
	ds_read_b64_tr_b16 v[94:95], v175 offset:0x1400
	ds_read_b64_tr_b16 v[96:97], v175 offset:0x1800
	ds_read_b64_tr_b16 v[98:99], v175 offset:0x1c00
	s_waitcnt lgkmcnt(0)
	s_nop 0
	v_mfma_f32_32x32x16_bf16 v[16:31], v[50:53], v[84:87], v[16:31]
	ds_read_b64_tr_b16 v[84:85], v175 offset:0x200
	ds_read_b64_tr_b16 v[86:87], v175 offset:0x600
	v_mfma_f32_32x32x16_bf16 v[16:31], v[54:57], v[88:91], v[16:31]
	ds_read_b64_tr_b16 v[88:89], v175 offset:0xa00
	ds_read_b64_tr_b16 v[90:91], v175 offset:0xe00
	v_mfma_f32_32x32x16_bf16 v[16:31], v[58:61], v[92:95], v[16:31]
	ds_read_b64_tr_b16 v[92:93], v175 offset:0x1200
	ds_read_b64_tr_b16 v[94:95], v175 offset:0x1600
	v_mfma_f32_32x32x16_bf16 v[16:31], v[80:83], v[96:99], v[16:31]
	ds_read_b64_tr_b16 v[96:97], v175 offset:0x1a00
	ds_read_b64_tr_b16 v[98:99], v175 offset:0x1e00
	s_waitcnt lgkmcnt(0)
	v_mfma_f32_32x32x16_bf16 v[0:15], v[50:53], v[84:87], v[0:15]
	v_max_f32_e32 v50, v65, v65
	v_max_f32_e32 v51, v64, v64
	v_max_f32_e32 v50, v51, v50
	v_max3_f32 v50, v50, v66, v67
	v_max3_f32 v50, v50, v68, v69
	v_max3_f32 v50, v50, v70, v71
	v_max3_f32 v50, v50, v72, v73
	v_mfma_f32_32x32x16_bf16 v[0:15], v[54:57], v[88:91], v[0:15]
	v_max3_f32 v50, v50, v74, v75
	v_max3_f32 v50, v50, v76, v77
	v_max3_f32 v50, v50, v78, v79
	v_max3_f32 v50, v50, v32, v33
	v_max3_f32 v50, v50, v34, v35
	v_max3_f32 v50, v50, v36, v37
	v_max3_f32 v50, v50, v38, v39
	v_mfma_f32_32x32x16_bf16 v[0:15], v[58:61], v[92:95], v[0:15]
	v_max3_f32 v50, v50, v40, v41
	v_max3_f32 v50, v50, v42, v43
	v_max3_f32 v50, v50, v44, v45
	v_max3_f32 v50, v50, v46, v47
	v_mov_b32_e32 v51, v50
	s_nop 1
	v_permlane32_swap_b32_e32 v50, v51
	v_mfma_f32_32x32x16_bf16 v[0:15], v[80:83], v[96:99], v[0:15]
	v_max_f32_e32 v51, v51, v51
	v_max_f32_e32 v50, v50, v50
	v_max_f32_e32 v51, v50, v51
	v_cmp_ge_f32_e32 vcc, s76, v51
	s_cmp_eq_u64 vcc, exec
	v_mov_b32_e32 v50, 1.0
	s_cbranch_scc0 .LBB0_756

.LBB0_753:
	v_exp_f32_e32 v64, v64
	v_exp_f32_e32 v80, v65
	v_exp_f32_e32 v62, v66
	v_exp_f32_e32 v65, v67
	v_exp_f32_e32 v60, v68
	v_exp_f32_e32 v66, v32
	v_add_f32_e32 v32, 0, v64
	v_exp_f32_e32 v63, v69
	v_add_f32_e32 v217, 0, v80
	v_exp_f32_e32 v59, v70
	v_add_f32_e32 v32, v62, v32
	v_exp_f32_e32 v61, v71
	v_add_f32_e32 v217, v65, v217
	v_exp_f32_e32 v56, v72
	v_add_f32_e32 v32, v60, v32
	v_exp_f32_e32 v58, v73
	v_add_f32_e32 v217, v63, v217
	v_exp_f32_e32 v54, v74
	v_add_f32_e32 v32, v59, v32
	v_exp_f32_e32 v57, v75
	v_add_f32_e32 v217, v61, v217
	v_exp_f32_e32 v52, v76
	v_add_f32_e32 v32, v56, v32
	v_exp_f32_e32 v55, v77
	v_add_f32_e32 v217, v58, v217
	v_exp_f32_e32 v51, v78
	v_add_f32_e32 v32, v54, v32
	v_exp_f32_e32 v53, v79
	v_add_f32_e32 v217, v57, v217
	v_add_f32_e32 v32, v52, v32
	v_exp_f32_e32 v67, v33
	v_add_f32_e32 v217, v55, v217
	v_exp_f32_e32 v68, v34
	v_add_f32_e32 v32, v51, v32
	v_exp_f32_e32 v69, v35
	v_add_f32_e32 v217, v53, v217
	v_exp_f32_e32 v70, v36
	v_add_f32_e32 v32, v66, v32
	v_exp_f32_e32 v71, v37
	v_add_f32_e32 v217, v67, v217
	v_exp_f32_e32 v72, v38
	v_add_f32_e32 v32, v68, v32
	v_exp_f32_e32 v73, v39
	v_add_f32_e32 v217, v69, v217
	v_exp_f32_e32 v74, v40
	v_add_f32_e32 v32, v70, v32
	v_exp_f32_e32 v75, v41
	v_add_f32_e32 v217, v71, v217
	v_exp_f32_e32 v76, v42
	v_add_f32_e32 v32, v72, v32
	v_exp_f32_e32 v77, v43
	v_add_f32_e32 v217, v73, v217
	v_exp_f32_e32 v78, v44
	v_add_f32_e32 v32, v74, v32
	v_exp_f32_e32 v79, v45
	v_add_f32_e32 v217, v75, v217
	v_exp_f32_e32 v46, v46
	v_add_f32_e32 v32, v76, v32
	v_exp_f32_e32 v47, v47
	v_add_f32_e32 v217, v77, v217
	v_add_f32_e32 v32, v78, v32
	v_add_f32_e32 v217, v79, v217
	v_add_f32_e32 v32, v46, v32
	v_add_f32_e32 v217, v47, v217
	v_add_f32_e32 v32, v217, v32
	v_mov_b32_e32 v33, v32
	s_nop 1
	v_permlane32_swap_b32_e32 v32, v33
	v_cvt_pk_bf16_f32 v34, v64, v80
	v_cvt_pk_bf16_f32 v35, v62, v65
	v_cvt_pk_bf16_f32 v36, v60, v63
	v_cvt_pk_bf16_f32 v37, v59, v61
	v_cvt_pk_bf16_f32 v38, v56, v58
	v_cvt_pk_bf16_f32 v39, v54, v57
	v_cvt_pk_bf16_f32 v40, v52, v55
	v_cvt_pk_bf16_f32 v41, v51, v53
	v_cvt_pk_bf16_f32 v42, v66, v67
	v_cvt_pk_bf16_f32 v43, v68, v69
	v_cvt_pk_bf16_f32 v44, v70, v71
	v_cvt_pk_bf16_f32 v45, v72, v73
	v_cvt_pk_bf16_f32 v52, v74, v75
	v_cvt_pk_bf16_f32 v53, v76, v77
	v_cvt_pk_bf16_f32 v54, v78, v79
	v_cvt_pk_bf16_f32 v55, v46, v47
	s_nop 0
	v_permlane32_swap_b32_e32 v34, v36
	v_permlane32_swap_b32_e32 v35, v37
	v_permlane32_swap_b32_e32 v38, v40
	v_permlane32_swap_b32_e32 v39, v41
	v_permlane32_swap_b32_e32 v42, v44
	v_permlane32_swap_b32_e32 v43, v45
	v_permlane32_swap_b32_e32 v52, v54
	v_permlane32_swap_b32_e32 v53, v55
	s_cmp_lg_u32 0, -1
	s_cselect_b32 s0, 0, 0
	s_addk_i32 s0, 0x2000
	v_add_u32_e32 v46, s0, v165
	ds_read_b64_tr_b16 v[56:57], v46 offset:0
	ds_read_b64_tr_b16 v[58:59], v46 offset:0x400
	ds_read_b64_tr_b16 v[60:61], v46 offset:0x800
	ds_read_b64_tr_b16 v[62:63], v46 offset:0xc00
	ds_read_b64_tr_b16 v[64:65], v46 offset:0x1000
	ds_read_b64_tr_b16 v[66:67], v46 offset:0x1400
	ds_read_b64_tr_b16 v[68:69], v46 offset:0x1800
	ds_read_b64_tr_b16 v[70:71], v46 offset:0x1c00
	s_waitcnt lgkmcnt(0)
	s_nop 0
	v_mfma_f32_32x32x16_bf16 v[16:31], v[34:37], v[56:59], v[16:31]
	ds_read_b64_tr_b16 v[56:57], v46 offset:0x200
	ds_read_b64_tr_b16 v[58:59], v46 offset:0x600
	v_mfma_f32_32x32x16_bf16 v[16:31], v[38:41], v[60:63], v[16:31]
	ds_read_b64_tr_b16 v[60:61], v46 offset:0xa00
	ds_read_b64_tr_b16 v[62:63], v46 offset:0xe00
	v_mfma_f32_32x32x16_bf16 v[16:31], v[42:45], v[64:67], v[16:31]
	ds_read_b64_tr_b16 v[64:65], v46 offset:0x1200
	ds_read_b64_tr_b16 v[66:67], v46 offset:0x1600
	v_mfma_f32_32x32x16_bf16 v[16:31], v[52:55], v[68:71], v[16:31]
	ds_read_b64_tr_b16 v[68:69], v46 offset:0x1a00
	ds_read_b64_tr_b16 v[70:71], v46 offset:0x1e00
	s_waitcnt lgkmcnt(0)
	v_mfma_f32_32x32x16_bf16 v[0:15], v[34:37], v[56:59], v[0:15]
	v_cmp_gt_u32_e32 vcc, 32, v151
	v_mfma_f32_32x32x16_bf16 v[0:15], v[38:41], v[60:63], v[0:15]
	v_mfma_f32_32x32x16_bf16 v[0:15], v[42:45], v[64:67], v[0:15]
	v_mfma_f32_32x32x16_bf16 v[0:15], v[52:55], v[68:71], v[0:15]
	s_and_saveexec_b64 s[0:1], vcc
	s_cbranch_execz .LBB0_694
	v_add_f32_e32 v34, v48, v49
	v_fmac_f32_e32 v34, v147, v181
	v_add_f32_e32 v32, v32, v33
	v_fmac_f32_e32 v32, v34, v50
	ds_write_b32 v164, v32 offset:49152
	s_branch .LBB0_694
